# v80 + GEMM unit-loop headers: the general division (v_rcp + corrections, 35 instrs) of the next-unit decode replaced by shift/mask (group size is 8 or 4)
# baseline (speedup 1.0000x reference)
.LBB0_178:
	s_ashr_i32 s10, s12, 3
	s_add_i32 s10, s14, s10
	s_mul_hi_i32 s11, s10, 0x51eb851f
	s_lshr_b32 s12, s11, 31
	s_ashr_i32 s11, s11, 6
	s_add_i32 s11, s11, s12
	s_lshl_b32 s12, s11, 3
	s_sub_i32 s13, 0x84, s12
	s_min_i32 s13, s13, 8
	s_mulk_i32 s11, 0xc8
	s_sub_i32 s11, s10, s11
	s_cmp_eq_u32 s13, 8
	s_cselect_b32 s14, 3, 2
	s_lshr_b32 s10, s11, s14
	s_lshl_b32 s13, s10, s14
	s_sub_i32 s11, s11, s13
	s_add_i32 s12, s12, s11

.LBB0_252:
	s_add_i32 s43, s43, 1
	s_mul_i32 s2, s43, s46
	s_mul_hi_u32 s3, s43, s34
	s_add_i32 s3, s3, s2
	s_mul_i32 s2, s43, s34
	s_add_u32 s24, s2, s35
	s_addc_u32 s25, s3, 0
	v_cmp_gt_i64_e32 vcc, s[24:25], v[162:163]
	v_cmp_lt_i64_e64 s[2:3], s[24:25], v[160:161]
	s_cbranch_vccnz .LBB0_254
	s_ashr_i32 s20, s24, 31
	s_lshr_b32 s20, s20, 29
	s_add_i32 s20, s24, s20
	s_ashr_i32 s21, s20, 3
	s_and_b32 s20, s20, -8
	s_sub_i32 s20, s24, s20
	s_cmp_lt_i32 s20, 0
	s_movk_i32 s22, 0x85
	s_cselect_b32 s22, s22, 0x84
	s_mul_i32 s20, s20, s22
	s_add_i32 s20, s20, s21
	s_ashr_i32 s21, s20, 31
	s_lshr_b32 s21, s21, 26
	s_add_i32 s21, s20, s21
	s_ashr_i32 s22, s21, 6
	s_lshl_b32 s22, s22, 3
	s_sub_i32 s23, 0x84, s22
	s_min_i32 s23, s23, 8
	s_andn2_b32 s21, s21, 63
	s_sub_i32 s21, s20, s21
	s_cmp_eq_u32 s23, 8
	s_cselect_b32 s24, 3, 2
	s_lshr_b32 s20, s21, s24
	s_lshl_b32 s23, s20, s24
	s_sub_i32 s21, s21, s23
	s_add_i32 s22, s22, s21

.LBB0_272:
	s_add_i32 s39, s39, 1
	s_mul_i32 s13, s39, s42
	s_mul_hi_u32 s14, s39, s34
	s_add_i32 s14, s14, s13
	s_mul_i32 s13, s39, s34
	s_add_u32 s18, s13, s26
	s_addc_u32 s19, s14, 0
	v_cmp_gt_i64_e64 s[20:21], s[18:19], 47
	v_cmp_lt_i64_e64 s[14:15], s[18:19], 48
	s_and_b64 vcc, exec, s[20:21]
	s_cbranch_vccnz .LBB0_274
	s_ashr_i32 s12, s18, 31
	s_lshr_b32 s12, s12, 29
	s_add_i32 s12, s18, s12
	s_ashr_i32 s13, s12, 3
	s_and_b32 s12, s12, -8
	s_sub_i32 s12, s18, s12
	s_cmp_lt_i32 s12, 0
	s_cselect_b32 s16, 7, 6
	s_mul_i32 s12, s12, s16
	s_add_i32 s12, s12, s13
	s_mul_hi_i32 s13, s12, 0x2aaaaaab
	s_lshr_b32 s16, s13, 31
	s_ashr_i32 s13, s13, 4
	s_add_i32 s13, s13, s16
	s_lshl_b32 s16, s13, 3
	s_sub_i32 s17, 4, s16
	s_min_i32 s17, s17, 8
	s_mulk_i32 s13, 0x60
	s_sub_i32 s13, s12, s13
	s_cmp_eq_u32 s17, 8
	s_cselect_b32 s18, 3, 2
	s_lshr_b32 s12, s13, s18
	s_lshl_b32 s17, s12, s18
	s_sub_i32 s13, s13, s17
	s_add_i32 s16, s16, s13

.LBB0_553:
	s_add_i32 s35, s35, 1
	s_mul_i32 s2, s35, s38
	s_mul_hi_u32 s3, s35, s39
	s_add_i32 s3, s3, s2
	s_mul_i32 s2, s35, s39
	s_add_u32 s16, s2, s83
	s_addc_u32 s17, s3, 0
	v_cmp_gt_i64_e32 vcc, s[16:17], v[162:163]
	v_cmp_lt_i64_e64 s[2:3], s[16:17], v[160:161]
	s_cbranch_vccnz .LBB0_555
	s_ashr_i32 s12, s16, 31
	s_lshr_b32 s12, s12, 29
	s_add_i32 s12, s16, s12
	s_ashr_i32 s13, s12, 3
	s_and_b32 s12, s12, -8
	s_sub_i32 s12, s16, s12
	s_cmp_lt_i32 s12, 0
	s_movk_i32 s14, 0xc1
	s_cselect_b32 s14, s14, 0xc0
	s_mul_i32 s12, s12, s14
	s_add_i32 s12, s12, s13
	s_mul_hi_i32 s13, s12, 0x2aaaaaab
	s_lshr_b32 s14, s13, 31
	s_ashr_i32 s13, s13, 4
	s_add_i32 s13, s13, s14
	s_lshl_b32 s14, s13, 3
	s_sub_i32 s15, 0x80, s14
	s_min_i32 s15, s15, 8
	s_mulk_i32 s13, 0x60
	s_sub_i32 s13, s12, s13
	s_cmp_eq_u32 s15, 8
	s_cselect_b32 s16, 3, 2
	s_lshr_b32 s12, s13, s16
	s_lshl_b32 s15, s12, s16
	s_sub_i32 s13, s13, s15
	s_add_i32 s14, s14, s13
	s_lshr_b32 s13, s14, 3
	s_lshr_b32 s15, s14, 4
	s_xor_b32 s13, s13, s15
	s_and_b32 s13, s13, 1
	s_xor_b32 s13, s13, 1
	s_mul_i32 s13, s13, 24
	s_xor_b32 s14, s14, s13

.LBB0_625:
	s_add_i32 s36, s36, 1
	s_mul_i32 s2, s36, s41
	s_mul_hi_u32 s3, s36, s42
	s_add_i32 s3, s3, s2
	s_mul_i32 s2, s36, s42
	s_add_u32 s20, s2, s83
	s_addc_u32 s21, s3, 0
	v_cmp_gt_i64_e32 vcc, s[20:21], v[142:143]
	v_cmp_lt_i64_e64 s[2:3], s[20:21], v[140:141]
	s_cbranch_vccnz .LBB0_627
	s_ashr_i32 s16, s20, 31
	s_lshr_b32 s16, s16, 29
	s_add_i32 s16, s20, s16
	s_ashr_i32 s17, s16, 3
	s_and_b32 s16, s16, -8
	s_sub_i32 s16, s20, s16
	s_cmp_lt_i32 s16, 0
	s_movk_i32 s18, 0x43
	s_cselect_b32 s18, s18, 0x42
	s_mul_i32 s16, s16, s18
	s_add_i32 s16, s16, s17
	s_ashr_i32 s17, s16, 31
	s_lshr_b32 s17, s17, 27
	s_add_i32 s17, s16, s17
	s_ashr_i32 s18, s17, 5
	s_lshl_b32 s18, s18, 3
	s_sub_i32 s19, 0x84, s18
	s_min_i32 s19, s19, 8
	s_andn2_b32 s17, s17, 31
	s_sub_i32 s17, s16, s17
	s_cmp_eq_u32 s19, 8
	s_cselect_b32 s20, 3, 2
	s_lshr_b32 s16, s17, s20
	s_lshl_b32 s19, s16, s20
	s_sub_i32 s17, s17, s19
	s_add_i32 s18, s18, s17
	s_and_b32 s19, s18, 0x8a
	s_cmp_eq_u32 s19, 0
	s_cselect_b32 s19, 16, 0
	s_xor_b32 s18, s18, s19

.LBB0_712:
	s_add_i32 s41, s41, 1
	s_mul_i32 s2, s41, s44
	s_mul_hi_u32 s3, s41, s45
	s_add_i32 s3, s3, s2
	s_mul_i32 s2, s41, s45
	s_add_u32 s24, s2, s83
	s_addc_u32 s25, s3, 0
	v_cmp_gt_i64_e32 vcc, s[24:25], v[166:167]
	v_cmp_lt_i64_e64 s[2:3], s[24:25], v[164:165]
	s_cbranch_vccnz .LBB0_714
	s_ashr_i32 s20, s24, 31
	s_lshr_b32 s20, s20, 29
	s_add_i32 s20, s24, s20
	s_ashr_i32 s21, s20, 3
	s_and_b32 s20, s20, -8
	s_sub_i32 s20, s24, s20
	s_cmp_lt_i32 s20, 0
	s_movk_i32 s22, 0x43
	s_cselect_b32 s22, s22, 0x42
	s_mul_i32 s20, s20, s22
	s_add_i32 s20, s20, s21
	s_ashr_i32 s21, s20, 31
	s_lshr_b32 s21, s21, 27
	s_add_i32 s21, s20, s21
	s_ashr_i32 s22, s21, 5
	s_lshl_b32 s22, s22, 3
	s_sub_i32 s23, 0x84, s22
	s_min_i32 s23, s23, 8
	s_andn2_b32 s21, s21, 31
	s_sub_i32 s21, s20, s21
	s_cmp_eq_u32 s23, 8
	s_cselect_b32 s24, 3, 2
	s_lshr_b32 s20, s21, s24
	s_lshl_b32 s23, s20, s24
	s_sub_i32 s21, s21, s23
	s_add_i32 s22, s22, s21

.LBB0_909:
	s_ashr_i32 s28, s30, 3
	s_add_i32 s28, s34, s28
	s_ashr_i32 s29, s28, 31
	s_lshr_b32 s29, s29, 27
	s_add_i32 s29, s28, s29
	s_ashr_i32 s30, s29, 5
	s_lshl_b32 s30, s30, 3
	s_sub_i32 s31, 0x80, s30
	s_min_i32 s31, s31, 8
	s_andn2_b32 s29, s29, 31
	s_sub_i32 s29, s28, s29
	s_cmp_eq_u32 s31, 8
	s_cselect_b32 s34, 3, 2
	s_lshr_b32 s28, s29, s34
	s_lshl_b32 s31, s28, s34
	s_sub_i32 s29, s29, s31
	s_add_i32 s30, s30, s29

.LBB0_1077:
	s_add_i32 s46, s46, 1
	s_mul_i32 s4, s46, s49
	s_mul_hi_u32 s5, s46, s50
	s_add_i32 s5, s5, s4
	s_mul_i32 s4, s46, s50
	s_add_u32 s28, s4, s83
	s_addc_u32 s29, s5, 0
	v_cmp_gt_i64_e32 vcc, s[28:29], v[142:143]
	v_cmp_lt_i64_e64 s[4:5], s[28:29], v[140:141]
	s_cbranch_vccnz .LBB0_1079
	s_ashr_i32 s24, s28, 31
	s_lshr_b32 s24, s24, 29
	s_add_i32 s24, s28, s24
	s_ashr_i32 s25, s24, 3
	s_and_b32 s24, s24, -8
	s_sub_i32 s24, s28, s24
	s_cmp_lt_i32 s24, 0
	s_cselect_b32 s26, s51, 0x108
	s_mul_i32 s24, s24, s26
	s_add_i32 s24, s24, s25
	s_ashr_i32 s25, s24, 31
	s_lshr_b32 s25, s25, 25
	s_add_i32 s25, s24, s25
	s_ashr_i32 s26, s25, 7
	s_lshl_b32 s26, s26, 3
	s_sub_i32 s27, 0x84, s26
	s_min_i32 s27, s27, 8
	s_and_b32 s25, s25, 0xffffff80
	s_sub_i32 s25, s24, s25
	s_cmp_eq_u32 s27, 8
	s_cselect_b32 s28, 3, 2
	s_lshr_b32 s24, s25, s28
	s_lshl_b32 s27, s24, s28
	s_sub_i32 s25, s25, s27
	s_add_i32 s26, s26, s25

.LBB0_1152:
	s_ashr_i32 s10, s16, 3
	s_add_i32 s10, s18, s10
	s_ashr_i32 s11, s10, 31
	s_lshr_b32 s11, s11, 27
	s_add_i32 s11, s10, s11
	s_ashr_i32 s16, s11, 5
	s_lshl_b32 s16, s16, 3
	s_sub_i32 s17, 0x80, s16
	s_min_i32 s17, s17, 8
	s_andn2_b32 s11, s11, 31
	s_sub_i32 s11, s10, s11
	s_cmp_eq_u32 s17, 8
	s_cselect_b32 s18, 3, 2
	s_lshr_b32 s10, s11, s18
	s_lshl_b32 s17, s10, s18
	s_sub_i32 s11, s11, s17
	s_add_i32 s16, s16, s11
